# v67 plus a workgroup barrier before every LDS-DMA staging block (the instances that follow a GEMM phase could overwrite LDS the trailing wave half was still reading)
# speedup vs baseline: 1.0148x; 1.0148x over previous
.LBB0_125:
	s_mul_hi_i32 s28, s61, 0x2aaaaaab
	s_lshr_b32 s29, s28, 31
	s_ashr_i32 s28, s28, 3
	s_add_i32 s31, s28, s29
	s_mul_i32 s28, s31, 0xffffffd0
	s_add_i32 s63, s61, s28
	s_mul_i32 s28, s31, 0xfffff400
	s_add_i32 s30, s27, s28
	s_and_b32 s28, s30, 0xffffff00
	s_and_b32 s29, s54, 0x60
	s_or_b32 s28, s28, s29
	s_ashr_i32 s29, s28, 31
	s_lshl_b64 s[34:35], s[28:29], 11
	s_add_u32 s34, s3, s34
	s_addc_u32 s35, s39, s35
	s_bitset1_b32 s28, 7
	s_ashr_i32 s29, s28, 31
	v_mov_b32_e32 v37, v228
	s_lshl_b64 s[28:29], s[28:29], 11
	s_add_u32 s36, s3, s28
	v_and_b32_e32 v122, 31, v37
	v_ashrrev_i32_e32 v123, 5, v37
	s_addc_u32 s37, s39, s29
	s_lshl_b32 s28, s31, 5
	s_ashr_i32 s29, s28, 31
	s_lshl_b64 s[64:65], s[28:29], 11
	s_add_u32 s64, s58, s64
	s_addc_u32 s65, s59, s65
	s_barrier
	s_mov_b32 s101, m0
	s_mul_i32 s100, s2, 0x180
	v_lshrrev_b32_e32 v14, 2, v37
	v_bfe_u32 v15, v37, 4, 2
	v_lshlrev_b32_e32 v14, 11, v14
	v_xor_b32_e32 v15, v15, v37
	v_bfe_u32 v16, v122, 2, 2
	v_and_b32_e32 v15, 3, v15
	v_xor_b32_e32 v16, v16, v123
	v_lshl_or_b32 v14, v15, 4, v14
	v_lshlrev_b32_e32 v16, 4, v16
	v_lshl_or_b32 v15, v122, 6, v16
	v_add_u32_e32 v15, s100, v15
	v_xor_b32_e32 v16, 32, v15
	s_add_u32 s98, s34, s0
	s_addc_u32 s99, s35, 0
	s_add_i32 m0, s100, 0x0
	s_nop 0
	global_load_lds_dwordx4 v14, s[98:99]
	s_add_u32 s98, s34, s0
	s_addc_u32 s99, s35, 0
	s_add_u32 s98, s98, 0x8000
	s_addc_u32 s99, s99, 0
	s_add_i32 m0, s100, 0x400
	s_nop 0
	global_load_lds_dwordx4 v14, s[98:99]
	s_add_u32 s98, s36, s0
	s_addc_u32 s99, s37, 0
	s_add_i32 m0, s100, 0x800
	s_nop 0
	global_load_lds_dwordx4 v14, s[98:99]
	s_add_u32 s98, s36, s0
	s_addc_u32 s99, s37, 0
	s_add_u32 s98, s98, 0x8000
	s_addc_u32 s99, s99, 0
	s_add_i32 m0, s100, 0xc00
	s_nop 0
	global_load_lds_dwordx4 v14, s[98:99]
	s_add_u32 s98, s64, s0
	s_addc_u32 s99, s65, 0
	s_add_u32 s98, s98, 0x2000000
	s_addc_u32 s99, s99, 0
	s_add_i32 m0, s100, 0x1000
	s_nop 0
	global_load_lds_dwordx4 v14, s[98:99]
	s_add_u32 s98, s64, s0
	s_addc_u32 s99, s65, 0
	s_add_u32 s98, s98, 0x2008000
	s_addc_u32 s99, s99, 0
	s_add_i32 m0, s100, 0x1400
	s_nop 0
	global_load_lds_dwordx4 v14, s[98:99]
	s_add_u32 s98, s34, s0
	s_addc_u32 s99, s35, 0
	s_add_u32 s98, s98, 0x40
	s_addc_u32 s99, s99, 0
	s_add_i32 m0, s100, 0x1800
	s_nop 0
	global_load_lds_dwordx4 v14, s[98:99]
	s_add_u32 s98, s34, s0
	s_addc_u32 s99, s35, 0
	s_add_u32 s98, s98, 0x8040
	s_addc_u32 s99, s99, 0
	s_add_i32 m0, s100, 0x1c00
	s_nop 0
	global_load_lds_dwordx4 v14, s[98:99]
	s_add_u32 s98, s36, s0
	s_addc_u32 s99, s37, 0
	s_add_u32 s98, s98, 0x40
	s_addc_u32 s99, s99, 0
	s_add_i32 m0, s100, 0x2000
	s_nop 0
	global_load_lds_dwordx4 v14, s[98:99]
	s_add_u32 s98, s36, s0
	s_addc_u32 s99, s37, 0
	s_add_u32 s98, s98, 0x8040
	s_addc_u32 s99, s99, 0
	s_add_i32 m0, s100, 0x2400
	s_nop 0
	global_load_lds_dwordx4 v14, s[98:99]
	s_add_u32 s98, s64, s0
	s_addc_u32 s99, s65, 0
	s_add_u32 s98, s98, 0x2000040
	s_addc_u32 s99, s99, 0
	s_add_i32 m0, s100, 0x2800
	s_nop 0
	global_load_lds_dwordx4 v14, s[98:99]
	s_add_u32 s98, s64, s0
	s_addc_u32 s99, s65, 0
	s_add_u32 s98, s98, 0x2008040
	s_addc_u32 s99, s99, 0
	s_add_i32 m0, s100, 0x2c00
	s_nop 0
	global_load_lds_dwordx4 v14, s[98:99]
	s_waitcnt vmcnt(6)
	ds_read_b128 v[2:5], v15
	ds_read_b128 v[6:9], v15 offset:2048
	ds_read_b128 v[10:13], v15 offset:4096
	ds_read_b128 v[38:41], v16
	ds_read_b128 v[42:45], v16 offset:2048
	ds_read_b128 v[46:49], v16 offset:4096
	s_waitcnt lgkmcnt(0)
	s_add_u32 s98, s34, s0
	s_addc_u32 s99, s35, 0
	s_add_u32 s98, s98, 0x80
	s_addc_u32 s99, s99, 0
	s_add_i32 m0, s100, 0x0
	s_nop 0
	global_load_lds_dwordx4 v14, s[98:99]
	s_add_u32 s98, s34, s0
	s_addc_u32 s99, s35, 0
	s_add_u32 s98, s98, 0x8080
	s_addc_u32 s99, s99, 0
	s_add_i32 m0, s100, 0x400
	s_nop 0
	global_load_lds_dwordx4 v14, s[98:99]
	s_add_u32 s98, s36, s0
	s_addc_u32 s99, s37, 0
	s_add_u32 s98, s98, 0x80
	s_addc_u32 s99, s99, 0
	s_add_i32 m0, s100, 0x800
	s_nop 0
	global_load_lds_dwordx4 v14, s[98:99]
	s_add_u32 s98, s36, s0
	s_addc_u32 s99, s37, 0
	s_add_u32 s98, s98, 0x8080
	s_addc_u32 s99, s99, 0
	s_add_i32 m0, s100, 0xc00
	s_nop 0
	global_load_lds_dwordx4 v14, s[98:99]
	s_add_u32 s98, s64, s0
	s_addc_u32 s99, s65, 0
	s_add_u32 s98, s98, 0x2000080
	s_addc_u32 s99, s99, 0
	s_add_i32 m0, s100, 0x1000
	s_nop 0
	global_load_lds_dwordx4 v14, s[98:99]
	s_add_u32 s98, s64, s0
	s_addc_u32 s99, s65, 0
	s_add_u32 s98, s98, 0x2008080
	s_addc_u32 s99, s99, 0
	s_add_i32 m0, s100, 0x1400
	s_nop 0
	global_load_lds_dwordx4 v14, s[98:99]
	s_waitcnt vmcnt(6)
	ds_read_b128 v[54:57], v15 offset:6144
	ds_read_b128 v[62:65], v15 offset:8192
	ds_read_b128 v[50:53], v15 offset:10240
	ds_read_b128 v[58:61], v16 offset:6144
	ds_read_b128 v[66:69], v16 offset:8192
	ds_read_b128 v[70:73], v16 offset:10240
	s_waitcnt lgkmcnt(0)
	s_add_u32 s98, s34, s0
	s_addc_u32 s99, s35, 0
	s_add_u32 s98, s98, 0xc0
	s_addc_u32 s99, s99, 0
	s_add_i32 m0, s100, 0x1800
	s_nop 0
	global_load_lds_dwordx4 v14, s[98:99]
	s_add_u32 s98, s34, s0
	s_addc_u32 s99, s35, 0
	s_add_u32 s98, s98, 0x80c0
	s_addc_u32 s99, s99, 0
	s_add_i32 m0, s100, 0x1c00
	s_nop 0
	global_load_lds_dwordx4 v14, s[98:99]
	s_add_u32 s98, s36, s0
	s_addc_u32 s99, s37, 0
	s_add_u32 s98, s98, 0xc0
	s_addc_u32 s99, s99, 0
	s_add_i32 m0, s100, 0x2000
	s_nop 0
	global_load_lds_dwordx4 v14, s[98:99]
	s_add_u32 s98, s36, s0
	s_addc_u32 s99, s37, 0
	s_add_u32 s98, s98, 0x80c0
	s_addc_u32 s99, s99, 0
	s_add_i32 m0, s100, 0x2400
	s_nop 0
	global_load_lds_dwordx4 v14, s[98:99]
	s_add_u32 s98, s64, s0
	s_addc_u32 s99, s65, 0
	s_add_u32 s98, s98, 0x20000c0
	s_addc_u32 s99, s99, 0
	s_add_i32 m0, s100, 0x2800
	s_nop 0
	global_load_lds_dwordx4 v14, s[98:99]
	s_add_u32 s98, s64, s0
	s_addc_u32 s99, s65, 0
	s_add_u32 s98, s98, 0x20080c0
	s_addc_u32 s99, s99, 0
	s_add_i32 m0, s100, 0x2c00
	s_nop 0
	global_load_lds_dwordx4 v14, s[98:99]
	s_waitcnt vmcnt(6)
	ds_read_b128 v[78:81], v15
	ds_read_b128 v[86:89], v15 offset:2048
	ds_read_b128 v[74:77], v15 offset:4096
	ds_read_b128 v[82:85], v16
	ds_read_b128 v[90:93], v16 offset:2048
	ds_read_b128 v[94:97], v16 offset:4096
	s_waitcnt vmcnt(0)
	ds_read_b128 v[102:105], v15 offset:6144
	ds_read_b128 v[110:113], v15 offset:8192
	ds_read_b128 v[98:101], v15 offset:10240
	ds_read_b128 v[106:109], v16 offset:6144
	ds_read_b128 v[114:117], v16 offset:8192
	ds_read_b128 v[118:121], v16 offset:10240
	s_mov_b32 m0, s101
	s_waitcnt lgkmcnt(0)
	v_mfma_f32_32x32x16_bf16 v[18:33], v[2:5], v[10:13], 0
	v_or_b32_e32 v34, s2, v122
	v_mul_lo_u32 v34, v34, s57
	s_ashr_i32 s64, s63, 3
	v_mfma_f32_32x32x16_bf16 v[2:17], v[6:9], v[10:13], 0
	v_mfma_f32_32x32x16_bf16 v[18:33], v[38:41], v[46:49], v[18:33]
	v_lshlrev_b32_e32 v38, 4, v123
	v_add3_u32 v34, 0, v34, v38
	v_mfma_f32_32x32x16_bf16 v[2:17], v[42:45], v[46:49], v[2:17]
	v_mfma_f32_32x32x16_bf16 v[18:33], v[54:57], v[50:53], v[18:33]
	v_mfma_f32_32x32x16_bf16 v[2:17], v[62:65], v[50:53], v[2:17]
	v_mfma_f32_32x32x16_bf16 v[18:33], v[58:61], v[70:73], v[18:33]
	v_mfma_f32_32x32x16_bf16 v[2:17], v[66:69], v[70:73], v[2:17]
	v_mfma_f32_32x32x16_bf16 v[18:33], v[78:81], v[74:77], v[18:33]
	v_mfma_f32_32x32x16_bf16 v[2:17], v[86:89], v[74:77], v[2:17]
	v_mfma_f32_32x32x16_bf16 v[18:33], v[82:85], v[94:97], v[18:33]
	v_mfma_f32_32x32x16_bf16 v[2:17], v[90:93], v[94:97], v[2:17]
	v_mfma_f32_32x32x16_bf16 v[18:33], v[102:105], v[98:101], v[18:33]
	v_mfma_f32_32x32x16_bf16 v[2:17], v[110:113], v[98:101], v[2:17]
	v_mfma_f32_32x32x16_bf16 v[18:33], v[106:109], v[118:121], v[18:33]
	v_mfma_f32_32x32x16_bf16 v[2:17], v[114:117], v[118:121], v[2:17]
	s_nop 10
	s_barrier
	ds_write_b128 v34, v[18:21]
	ds_write_b128 v34, v[2:5] offset:128
	ds_write_b128 v34, v[22:25] offset:32
	ds_write_b128 v34, v[6:9] offset:160
	ds_write_b128 v34, v[26:29] offset:64
	ds_write_b128 v34, v[10:13] offset:192
	ds_write_b128 v34, v[30:33] offset:96
	ds_write_b128 v34, v[14:17] offset:224
	v_add_u32_e32 v2, s26, v37
	v_ashrrev_i32_e32 v13, 4, v2
	v_lshlrev_b32_e32 v2, 2, v37
	v_and_b32_e32 v20, 60, v2
	v_lshlrev_b32_e32 v12, 2, v20
	v_mul_lo_u32 v2, v13, s57
	v_add3_u32 v21, 0, v12, v2
	s_waitcnt lgkmcnt(0)
	s_barrier
	ds_read_b128 v[2:5], v21
	ds_read_b128 v[6:9], v21 offset:8704
	ds_read_b128 v[14:17], v21 offset:17408
	s_waitcnt lgkmcnt(2)
	v_pk_add_f32 v[4:5], v[4:5], 0 op_sel_hi:[1,0]
	v_pk_add_f32 v[10:11], v[2:3], 0 op_sel_hi:[1,0]
	s_waitcnt lgkmcnt(1)
	v_pk_add_f32 v[8:9], v[4:5], v[8:9]
	ds_read_b128 v[2:5], v21 offset:26112
	v_pk_add_f32 v[10:11], v[10:11], v[6:7]
	s_waitcnt lgkmcnt(1)
	v_pk_add_f32 v[16:17], v[8:9], v[16:17]
	ds_read_b128 v[6:9], v21 offset:34816
	v_pk_add_f32 v[10:11], v[10:11], v[14:15]
	s_waitcnt lgkmcnt(1)
	v_pk_add_f32 v[14:15], v[16:17], v[4:5]
	v_pk_add_f32 v[16:17], v[10:11], v[2:3]
	ds_read_b128 v[2:5], v21 offset:43520
	s_waitcnt lgkmcnt(1)
	v_pk_add_f32 v[18:19], v[14:15], v[8:9]
	ds_read_b128 v[8:11], v21 offset:52224
	v_pk_add_f32 v[6:7], v[16:17], v[6:7]
	ds_read_b128 v[14:17], v21 offset:60928
	s_waitcnt lgkmcnt(2)
	v_pk_add_f32 v[2:3], v[6:7], v[2:3]
	v_add_u32_e32 v6, s28, v13
	v_pk_add_f32 v[4:5], v[18:19], v[4:5]
	v_ashrrev_i32_e32 v7, 31, v6
	s_waitcnt lgkmcnt(1)
	v_pk_add_f32 v[4:5], v[4:5], v[10:11]
	v_pk_add_f32 v[2:3], v[2:3], v[8:9]
	v_lshlrev_b64 v[10:11], 9, v[6:7]
	s_and_b32 s28, s30, 0x1c0
	s_waitcnt lgkmcnt(0)
	v_pk_add_f32 v[4:5], v[4:5], v[16:17]
	v_pk_add_f32 v[2:3], v[2:3], v[14:15]
	v_or3_b32 v10, v10, s28, v20
	s_cmp_gt_i32 s64, 1
	s_mov_b64 s[28:29], -1
	s_barrier
	s_cbranch_scc0 .LBB0_138
	s_mov_b64 s[36:37], -1
	s_mov_b64 s[28:29], 0
	s_cmp_lt_i32 s64, 4
	s_mov_b64 s[30:31], 0
	s_mov_b64 s[34:35], 0
	s_cbranch_scc1 .LBB0_131
	s_cmp_lg_u32 s64, 4
	s_mov_b64 s[30:31], -1
	s_cselect_b64 s[34:35], -1, 0
	s_cbranch_execz .LBB0_132

.LBB0_666:
	s_mul_hi_i32 s12, s57, 0x2aaaaaab
	s_lshr_b32 s13, s12, 31
	s_ashr_i32 s12, s12, 3
	s_add_i32 s27, s12, s13
	s_mul_i32 s12, s27, 0xffffffd0
	s_add_i32 s60, s57, s12
	s_mul_i32 s12, s27, 0xfffff400
	s_add_i32 s26, s34, s12
	s_and_b32 s12, s26, 0xffffff00
	s_and_b32 s13, s36, 0x60
	s_or_b32 s12, s12, s13
	s_ashr_i32 s13, s12, 31
	s_lshl_b64 s[28:29], s[12:13], 11
	s_add_u32 s28, s3, s28
	s_addc_u32 s29, s39, s29
	s_bitset1_b32 s12, 7
	s_ashr_i32 s13, s12, 31
	v_mov_b32_e32 v37, v228
	s_lshl_b64 s[12:13], s[12:13], 11
	s_add_u32 s30, s3, s12
	v_and_b32_e32 v122, 31, v37
	v_ashrrev_i32_e32 v123, 5, v37
	s_addc_u32 s31, s39, s13
	s_lshl_b32 s12, s27, 5
	s_ashr_i32 s13, s12, 31
	s_lshl_b64 s[64:65], s[12:13], 11
	s_add_u32 s64, s58, s64
	s_addc_u32 s65, s59, s65
	s_barrier
	s_mov_b32 s101, m0
	s_mul_i32 s100, s2, 0x180
	v_lshrrev_b32_e32 v14, 2, v37
	v_bfe_u32 v15, v37, 4, 2
	v_lshlrev_b32_e32 v14, 11, v14
	v_xor_b32_e32 v15, v15, v37
	v_bfe_u32 v16, v122, 2, 2
	v_and_b32_e32 v15, 3, v15
	v_xor_b32_e32 v16, v16, v123
	v_lshl_or_b32 v14, v15, 4, v14
	v_lshlrev_b32_e32 v16, 4, v16
	v_lshl_or_b32 v15, v122, 6, v16
	v_add_u32_e32 v15, s100, v15
	v_xor_b32_e32 v16, 32, v15
	s_add_u32 s98, s28, s0
	s_addc_u32 s99, s29, 0
	s_add_i32 m0, s100, 0x0
	s_nop 0
	global_load_lds_dwordx4 v14, s[98:99]
	s_add_u32 s98, s28, s0
	s_addc_u32 s99, s29, 0
	s_add_u32 s98, s98, 0x8000
	s_addc_u32 s99, s99, 0
	s_add_i32 m0, s100, 0x400
	s_nop 0
	global_load_lds_dwordx4 v14, s[98:99]
	s_add_u32 s98, s30, s0
	s_addc_u32 s99, s31, 0
	s_add_i32 m0, s100, 0x800
	s_nop 0
	global_load_lds_dwordx4 v14, s[98:99]
	s_add_u32 s98, s30, s0
	s_addc_u32 s99, s31, 0
	s_add_u32 s98, s98, 0x8000
	s_addc_u32 s99, s99, 0
	s_add_i32 m0, s100, 0xc00
	s_nop 0
	global_load_lds_dwordx4 v14, s[98:99]
	s_add_u32 s98, s64, s0
	s_addc_u32 s99, s65, 0
	s_add_u32 s98, s98, 0x2000000
	s_addc_u32 s99, s99, 0
	s_add_i32 m0, s100, 0x1000
	s_nop 0
	global_load_lds_dwordx4 v14, s[98:99]
	s_add_u32 s98, s64, s0
	s_addc_u32 s99, s65, 0
	s_add_u32 s98, s98, 0x2008000
	s_addc_u32 s99, s99, 0
	s_add_i32 m0, s100, 0x1400
	s_nop 0
	global_load_lds_dwordx4 v14, s[98:99]
	s_add_u32 s98, s28, s0
	s_addc_u32 s99, s29, 0
	s_add_u32 s98, s98, 0x40
	s_addc_u32 s99, s99, 0
	s_add_i32 m0, s100, 0x1800
	s_nop 0
	global_load_lds_dwordx4 v14, s[98:99]
	s_add_u32 s98, s28, s0
	s_addc_u32 s99, s29, 0
	s_add_u32 s98, s98, 0x8040
	s_addc_u32 s99, s99, 0
	s_add_i32 m0, s100, 0x1c00
	s_nop 0
	global_load_lds_dwordx4 v14, s[98:99]
	s_add_u32 s98, s30, s0
	s_addc_u32 s99, s31, 0
	s_add_u32 s98, s98, 0x40
	s_addc_u32 s99, s99, 0
	s_add_i32 m0, s100, 0x2000
	s_nop 0
	global_load_lds_dwordx4 v14, s[98:99]
	s_add_u32 s98, s30, s0
	s_addc_u32 s99, s31, 0
	s_add_u32 s98, s98, 0x8040
	s_addc_u32 s99, s99, 0
	s_add_i32 m0, s100, 0x2400
	s_nop 0
	global_load_lds_dwordx4 v14, s[98:99]
	s_add_u32 s98, s64, s0
	s_addc_u32 s99, s65, 0
	s_add_u32 s98, s98, 0x2000040
	s_addc_u32 s99, s99, 0
	s_add_i32 m0, s100, 0x2800
	s_nop 0
	global_load_lds_dwordx4 v14, s[98:99]
	s_add_u32 s98, s64, s0
	s_addc_u32 s99, s65, 0
	s_add_u32 s98, s98, 0x2008040
	s_addc_u32 s99, s99, 0
	s_add_i32 m0, s100, 0x2c00
	s_nop 0
	global_load_lds_dwordx4 v14, s[98:99]
	s_waitcnt vmcnt(6)
	ds_read_b128 v[2:5], v15
	ds_read_b128 v[6:9], v15 offset:2048
	ds_read_b128 v[10:13], v15 offset:4096
	ds_read_b128 v[38:41], v16
	ds_read_b128 v[42:45], v16 offset:2048
	ds_read_b128 v[46:49], v16 offset:4096
	s_waitcnt lgkmcnt(0)
	s_add_u32 s98, s28, s0
	s_addc_u32 s99, s29, 0
	s_add_u32 s98, s98, 0x80
	s_addc_u32 s99, s99, 0
	s_add_i32 m0, s100, 0x0
	s_nop 0
	global_load_lds_dwordx4 v14, s[98:99]
	s_add_u32 s98, s28, s0
	s_addc_u32 s99, s29, 0
	s_add_u32 s98, s98, 0x8080
	s_addc_u32 s99, s99, 0
	s_add_i32 m0, s100, 0x400
	s_nop 0
	global_load_lds_dwordx4 v14, s[98:99]
	s_add_u32 s98, s30, s0
	s_addc_u32 s99, s31, 0
	s_add_u32 s98, s98, 0x80
	s_addc_u32 s99, s99, 0
	s_add_i32 m0, s100, 0x800
	s_nop 0
	global_load_lds_dwordx4 v14, s[98:99]
	s_add_u32 s98, s30, s0
	s_addc_u32 s99, s31, 0
	s_add_u32 s98, s98, 0x8080
	s_addc_u32 s99, s99, 0
	s_add_i32 m0, s100, 0xc00
	s_nop 0
	global_load_lds_dwordx4 v14, s[98:99]
	s_add_u32 s98, s64, s0
	s_addc_u32 s99, s65, 0
	s_add_u32 s98, s98, 0x2000080
	s_addc_u32 s99, s99, 0
	s_add_i32 m0, s100, 0x1000
	s_nop 0
	global_load_lds_dwordx4 v14, s[98:99]
	s_add_u32 s98, s64, s0
	s_addc_u32 s99, s65, 0
	s_add_u32 s98, s98, 0x2008080
	s_addc_u32 s99, s99, 0
	s_add_i32 m0, s100, 0x1400
	s_nop 0
	global_load_lds_dwordx4 v14, s[98:99]
	s_waitcnt vmcnt(6)
	ds_read_b128 v[54:57], v15 offset:6144
	ds_read_b128 v[62:65], v15 offset:8192
	ds_read_b128 v[50:53], v15 offset:10240
	ds_read_b128 v[58:61], v16 offset:6144
	ds_read_b128 v[66:69], v16 offset:8192
	ds_read_b128 v[70:73], v16 offset:10240
	s_waitcnt lgkmcnt(0)
	s_add_u32 s98, s28, s0
	s_addc_u32 s99, s29, 0
	s_add_u32 s98, s98, 0xc0
	s_addc_u32 s99, s99, 0
	s_add_i32 m0, s100, 0x1800
	s_nop 0
	global_load_lds_dwordx4 v14, s[98:99]
	s_add_u32 s98, s28, s0
	s_addc_u32 s99, s29, 0
	s_add_u32 s98, s98, 0x80c0
	s_addc_u32 s99, s99, 0
	s_add_i32 m0, s100, 0x1c00
	s_nop 0
	global_load_lds_dwordx4 v14, s[98:99]
	s_add_u32 s98, s30, s0
	s_addc_u32 s99, s31, 0
	s_add_u32 s98, s98, 0xc0
	s_addc_u32 s99, s99, 0
	s_add_i32 m0, s100, 0x2000
	s_nop 0
	global_load_lds_dwordx4 v14, s[98:99]
	s_add_u32 s98, s30, s0
	s_addc_u32 s99, s31, 0
	s_add_u32 s98, s98, 0x80c0
	s_addc_u32 s99, s99, 0
	s_add_i32 m0, s100, 0x2400
	s_nop 0
	global_load_lds_dwordx4 v14, s[98:99]
	s_add_u32 s98, s64, s0
	s_addc_u32 s99, s65, 0
	s_add_u32 s98, s98, 0x20000c0
	s_addc_u32 s99, s99, 0
	s_add_i32 m0, s100, 0x2800
	s_nop 0
	global_load_lds_dwordx4 v14, s[98:99]
	s_add_u32 s98, s64, s0
	s_addc_u32 s99, s65, 0
	s_add_u32 s98, s98, 0x20080c0
	s_addc_u32 s99, s99, 0
	s_add_i32 m0, s100, 0x2c00
	s_nop 0
	global_load_lds_dwordx4 v14, s[98:99]
	s_waitcnt vmcnt(6)
	ds_read_b128 v[78:81], v15
	ds_read_b128 v[86:89], v15 offset:2048
	ds_read_b128 v[74:77], v15 offset:4096
	ds_read_b128 v[82:85], v16
	ds_read_b128 v[90:93], v16 offset:2048
	ds_read_b128 v[94:97], v16 offset:4096
	s_waitcnt vmcnt(0)
	ds_read_b128 v[102:105], v15 offset:6144
	ds_read_b128 v[110:113], v15 offset:8192
	ds_read_b128 v[98:101], v15 offset:10240
	ds_read_b128 v[106:109], v16 offset:6144
	ds_read_b128 v[114:117], v16 offset:8192
	ds_read_b128 v[118:121], v16 offset:10240
	s_mov_b32 m0, s101
	s_waitcnt lgkmcnt(0)
	v_mfma_f32_32x32x16_bf16 v[18:33], v[2:5], v[10:13], 0
	v_or_b32_e32 v34, s2, v122
	v_mul_lo_u32 v34, v34, s55
	s_ashr_i32 s61, s60, 3
	v_mfma_f32_32x32x16_bf16 v[2:17], v[6:9], v[10:13], 0
	v_mfma_f32_32x32x16_bf16 v[18:33], v[38:41], v[46:49], v[18:33]
	v_lshlrev_b32_e32 v38, 4, v123
	v_add3_u32 v34, 0, v34, v38
	v_mfma_f32_32x32x16_bf16 v[2:17], v[42:45], v[46:49], v[2:17]
	v_mfma_f32_32x32x16_bf16 v[18:33], v[54:57], v[50:53], v[18:33]
	v_mfma_f32_32x32x16_bf16 v[2:17], v[62:65], v[50:53], v[2:17]
	v_mfma_f32_32x32x16_bf16 v[18:33], v[58:61], v[70:73], v[18:33]
	v_mfma_f32_32x32x16_bf16 v[2:17], v[66:69], v[70:73], v[2:17]
	v_mfma_f32_32x32x16_bf16 v[18:33], v[78:81], v[74:77], v[18:33]
	v_mfma_f32_32x32x16_bf16 v[2:17], v[86:89], v[74:77], v[2:17]
	v_mfma_f32_32x32x16_bf16 v[18:33], v[82:85], v[94:97], v[18:33]
	v_mfma_f32_32x32x16_bf16 v[2:17], v[90:93], v[94:97], v[2:17]
	v_mfma_f32_32x32x16_bf16 v[18:33], v[102:105], v[98:101], v[18:33]
	v_mfma_f32_32x32x16_bf16 v[2:17], v[110:113], v[98:101], v[2:17]
	v_mfma_f32_32x32x16_bf16 v[18:33], v[106:109], v[118:121], v[18:33]
	v_mfma_f32_32x32x16_bf16 v[2:17], v[114:117], v[118:121], v[2:17]
	s_nop 10
	s_barrier
	ds_write_b128 v34, v[18:21]
	ds_write_b128 v34, v[2:5] offset:128
	ds_write_b128 v34, v[22:25] offset:32
	ds_write_b128 v34, v[6:9] offset:160
	ds_write_b128 v34, v[26:29] offset:64
	ds_write_b128 v34, v[10:13] offset:192
	ds_write_b128 v34, v[30:33] offset:96
	ds_write_b128 v34, v[14:17] offset:224
	v_add_u32_e32 v2, s33, v37
	v_ashrrev_i32_e32 v13, 4, v2
	v_lshlrev_b32_e32 v2, 2, v37
	v_and_b32_e32 v20, 60, v2
	v_lshlrev_b32_e32 v12, 2, v20
	v_mul_lo_u32 v2, v13, s55
	v_add3_u32 v21, 0, v12, v2
	s_waitcnt lgkmcnt(0)
	s_barrier
	ds_read_b128 v[2:5], v21
	ds_read_b128 v[6:9], v21 offset:8704
	ds_read_b128 v[14:17], v21 offset:17408
	s_waitcnt lgkmcnt(2)
	v_pk_add_f32 v[4:5], v[4:5], 0 op_sel_hi:[1,0]
	v_pk_add_f32 v[10:11], v[2:3], 0 op_sel_hi:[1,0]
	s_waitcnt lgkmcnt(1)
	v_pk_add_f32 v[8:9], v[4:5], v[8:9]
	ds_read_b128 v[2:5], v21 offset:26112
	v_pk_add_f32 v[10:11], v[10:11], v[6:7]
	s_waitcnt lgkmcnt(1)
	v_pk_add_f32 v[16:17], v[8:9], v[16:17]
	ds_read_b128 v[6:9], v21 offset:34816
	v_pk_add_f32 v[10:11], v[10:11], v[14:15]
	s_waitcnt lgkmcnt(1)
	v_pk_add_f32 v[14:15], v[16:17], v[4:5]
	v_pk_add_f32 v[16:17], v[10:11], v[2:3]
	ds_read_b128 v[2:5], v21 offset:43520
	s_waitcnt lgkmcnt(1)
	v_pk_add_f32 v[18:19], v[14:15], v[8:9]
	ds_read_b128 v[8:11], v21 offset:52224
	v_pk_add_f32 v[6:7], v[16:17], v[6:7]
	ds_read_b128 v[14:17], v21 offset:60928
	s_waitcnt lgkmcnt(2)
	v_pk_add_f32 v[2:3], v[6:7], v[2:3]
	v_add_u32_e32 v6, s12, v13
	v_pk_add_f32 v[4:5], v[18:19], v[4:5]
	v_ashrrev_i32_e32 v7, 31, v6
	s_waitcnt lgkmcnt(1)
	v_pk_add_f32 v[4:5], v[4:5], v[10:11]
	v_pk_add_f32 v[2:3], v[2:3], v[8:9]
	v_lshlrev_b64 v[10:11], 9, v[6:7]
	s_and_b32 s12, s26, 0x1c0
	s_waitcnt lgkmcnt(0)
	v_pk_add_f32 v[4:5], v[4:5], v[16:17]
	v_pk_add_f32 v[2:3], v[2:3], v[14:15]
	v_or3_b32 v10, v10, s12, v20
	s_cmp_gt_i32 s61, 1
	s_mov_b64 s[12:13], -1
	s_barrier
	s_cbranch_scc0 .LBB0_679
	s_mov_b64 s[30:31], -1
	s_mov_b64 s[12:13], 0
	s_cmp_lt_i32 s61, 4
	s_mov_b64 s[26:27], 0
	s_mov_b64 s[28:29], 0
	s_cbranch_scc1 .LBB0_672
	s_cmp_lg_u32 s61, 4
	s_mov_b64 s[26:27], -1
	s_cselect_b64 s[28:29], -1, 0
	s_cbranch_execz .LBB0_673

.LBB0_1165:
	s_and_b32 s30, s25, 7
	s_lshl_b32 s18, s30, 16
	s_add_u32 s26, s44, s18
	v_mov_b32_e32 v1, v228
	s_addc_u32 s27, s45, 0
	s_and_b32 s18, s21, 0xffffffe0
	s_ashr_i32 s19, s18, 31
	v_and_b32_e32 v72, 31, v1
	v_ashrrev_i32_e32 v73, 5, v1
	s_lshl_b64 s[28:29], s[18:19], 10
	s_add_u32 s28, s8, s28
	s_addc_u32 s29, s9, s29
	s_barrier
	s_mov_b32 s101, m0
	s_mul_i32 s100, s20, 0x180
	v_lshrrev_b32_e32 v24, 2, v1
	v_bfe_u32 v25, v1, 4, 2
	v_lshlrev_b32_e32 v24, 10, v24
	v_xor_b32_e32 v25, v25, v1
	v_bfe_u32 v26, v72, 2, 2
	v_and_b32_e32 v25, 3, v25
	v_xor_b32_e32 v26, v26, v73
	v_lshl_or_b32 v24, v25, 4, v24
	v_lshlrev_b32_e32 v26, 4, v26
	v_lshl_or_b32 v25, v72, 6, v26
	v_add_u32_e32 v25, s100, v25
	v_xor_b32_e32 v26, 32, v25
	s_add_u32 s98, s26, s4
	s_addc_u32 s99, s27, 0
	s_add_i32 m0, s100, 0x0
	s_nop 0
	global_load_lds_dwordx4 v24, s[98:99]
	s_add_u32 s98, s26, s4
	s_addc_u32 s99, s27, 0
	s_add_u32 s98, s98, 0x4000
	s_addc_u32 s99, s99, 0
	s_add_i32 m0, s100, 0x400
	s_nop 0
	global_load_lds_dwordx4 v24, s[98:99]
	s_add_u32 s98, s26, s4
	s_addc_u32 s99, s27, 0
	s_add_u32 s98, s98, 0x8000
	s_addc_u32 s99, s99, 0
	s_add_i32 m0, s100, 0x800
	s_nop 0
	global_load_lds_dwordx4 v24, s[98:99]
	s_add_u32 s98, s26, s4
	s_addc_u32 s99, s27, 0
	s_add_u32 s98, s98, 0xc000
	s_addc_u32 s99, s99, 0
	s_add_i32 m0, s100, 0xc00
	s_nop 0
	global_load_lds_dwordx4 v24, s[98:99]
	s_add_u32 s98, s28, s4
	s_addc_u32 s99, s29, 0
	s_add_u32 s98, s98, 0x1000000
	s_addc_u32 s99, s99, 0
	s_add_i32 m0, s100, 0x1000
	s_nop 0
	global_load_lds_dwordx4 v24, s[98:99]
	s_add_u32 s98, s28, s4
	s_addc_u32 s99, s29, 0
	s_add_u32 s98, s98, 0x1004000
	s_addc_u32 s99, s99, 0
	s_add_i32 m0, s100, 0x1400
	s_nop 0
	global_load_lds_dwordx4 v24, s[98:99]
	s_add_u32 s98, s26, s4
	s_addc_u32 s99, s27, 0
	s_add_u32 s98, s98, 0x40
	s_addc_u32 s99, s99, 0
	s_add_i32 m0, s100, 0x1800
	s_nop 0
	global_load_lds_dwordx4 v24, s[98:99]
	s_add_u32 s98, s26, s4
	s_addc_u32 s99, s27, 0
	s_add_u32 s98, s98, 0x4040
	s_addc_u32 s99, s99, 0
	s_add_i32 m0, s100, 0x1c00
	s_nop 0
	global_load_lds_dwordx4 v24, s[98:99]
	s_add_u32 s98, s26, s4
	s_addc_u32 s99, s27, 0
	s_add_u32 s98, s98, 0x8040
	s_addc_u32 s99, s99, 0
	s_add_i32 m0, s100, 0x2000
	s_nop 0
	global_load_lds_dwordx4 v24, s[98:99]
	s_add_u32 s98, s26, s4
	s_addc_u32 s99, s27, 0
	s_add_u32 s98, s98, 0xc040
	s_addc_u32 s99, s99, 0
	s_add_i32 m0, s100, 0x2400
	s_nop 0
	global_load_lds_dwordx4 v24, s[98:99]
	s_add_u32 s98, s28, s4
	s_addc_u32 s99, s29, 0
	s_add_u32 s98, s98, 0x1000040
	s_addc_u32 s99, s99, 0
	s_add_i32 m0, s100, 0x2800
	s_nop 0
	global_load_lds_dwordx4 v24, s[98:99]
	s_add_u32 s98, s28, s4
	s_addc_u32 s99, s29, 0
	s_add_u32 s98, s98, 0x1004040
	s_addc_u32 s99, s99, 0
	s_add_i32 m0, s100, 0x2c00
	s_nop 0
	global_load_lds_dwordx4 v24, s[98:99]
	s_waitcnt vmcnt(6)
	ds_read_b128 v[10:13], v25
	ds_read_b128 v[2:5], v25 offset:2048
	ds_read_b128 v[6:9], v25 offset:4096
	ds_read_b128 v[36:39], v26
	ds_read_b128 v[40:43], v26 offset:2048
	ds_read_b128 v[56:59], v26 offset:4096
	s_waitcnt vmcnt(0)
	ds_read_b128 v[48:51], v25 offset:6144
	ds_read_b128 v[44:47], v25 offset:8192
	ds_read_b128 v[64:67], v25 offset:10240
	ds_read_b128 v[52:55], v26 offset:6144
	ds_read_b128 v[60:63], v26 offset:8192
	ds_read_b128 v[68:71], v26 offset:10240
	s_mov_b32 m0, s101
	s_waitcnt lgkmcnt(0)
	v_mfma_f32_32x32x16_bf16 v[18:33], v[10:13], v[6:9], 0
	v_or_b32_e32 v34, s20, v72
	v_mul_lo_u32 v34, v34, s24
	s_add_u32 s18, s18, 0x4000
	s_addc_u32 s19, s19, 0
	s_add_i32 s25, s25, s46
	s_add_i32 s21, s21, s22
	s_cmpk_lt_i32 s25, 0x80
	v_mfma_f32_32x32x16_bf16 v[2:17], v[2:5], v[6:9], 0
	v_mfma_f32_32x32x16_bf16 v[18:33], v[36:39], v[56:59], v[18:33]
	v_lshlrev_b32_e32 v36, 4, v73
	v_add3_u32 v34, 0, v34, v36
	v_mfma_f32_32x32x16_bf16 v[2:17], v[40:43], v[56:59], v[2:17]
	v_mfma_f32_32x32x16_bf16 v[18:33], v[48:51], v[64:67], v[18:33]
	v_mfma_f32_32x32x16_bf16 v[2:17], v[44:47], v[64:67], v[2:17]
	v_mfma_f32_32x32x16_bf16 v[18:33], v[52:55], v[68:71], v[18:33]
	v_mfma_f32_32x32x16_bf16 v[2:17], v[60:63], v[68:71], v[2:17]
	s_nop 10
	s_barrier
	ds_write_b128 v34, v[18:21]
	ds_write_b128 v34, v[2:5] offset:128
	ds_write_b128 v34, v[22:25] offset:32
	ds_write_b128 v34, v[6:9] offset:160
	ds_write_b128 v34, v[26:29] offset:64
	ds_write_b128 v34, v[10:13] offset:192
	ds_write_b128 v34, v[30:33] offset:96
	ds_write_b128 v34, v[14:17] offset:224
	v_add_u32_e32 v2, s0, v1
	v_lshlrev_b32_e32 v1, 2, v1
	v_ashrrev_i32_e32 v36, 4, v2
	v_and_b32_e32 v1, 60, v1
	v_lshlrev_b32_e32 v2, 2, v1
	v_mul_lo_u32 v3, v36, s24
	v_lshl_or_b32 v1, s30, 6, v1
	v_add3_u32 v30, 0, v2, v3
	v_ashrrev_i32_e32 v37, 31, v36
	v_lshlrev_b32_e32 v34, 2, v1
	s_waitcnt lgkmcnt(0)
	s_barrier
	ds_read_b128 v[2:5], v30
	ds_read_b128 v[6:9], v30 offset:8704
	ds_read_b128 v[10:13], v30 offset:17408
	ds_read_b128 v[14:17], v30 offset:26112
	ds_read_b128 v[18:21], v30 offset:34816
	ds_read_b128 v[22:25], v30 offset:43520
	ds_read_b128 v[26:29], v30 offset:52224
	ds_read_b128 v[30:33], v30 offset:60928
	s_waitcnt lgkmcnt(0)
	s_barrier
	v_lshl_add_u64 v[40:41], s[18:19], 0, v[36:37]
	global_load_dwordx4 v[36:39], v34, s[56:57]
	v_lshlrev_b64 v[42:43], 10, v[40:41]
	v_lshl_add_u64 v[44:45], s[8:9], 0, v[42:43]
	v_lshlrev_b32_e32 v34, 1, v1
	v_lshl_add_u64 v[44:45], v[44:45], 0, v[34:35]
	v_lshl_add_u64 v[42:43], s[6:7], 0, v[42:43]
	global_load_dwordx2 v[44:45], v[44:45], off
	v_lshl_add_u64 v[42:43], v[42:43], 0, v[34:35]
	global_load_dwordx2 v[42:43], v[42:43], off
	v_pk_add_f32 v[4:5], v[4:5], 0 op_sel_hi:[1,0]
	v_pk_add_f32 v[2:3], v[2:3], 0 op_sel_hi:[1,0]
	v_pk_add_f32 v[4:5], v[4:5], v[8:9]
	v_pk_add_f32 v[2:3], v[2:3], v[6:7]
	v_pk_add_f32 v[4:5], v[4:5], v[12:13]
	v_pk_add_f32 v[2:3], v[2:3], v[10:11]
	v_pk_add_f32 v[4:5], v[4:5], v[16:17]
	v_pk_add_f32 v[2:3], v[2:3], v[14:15]
	v_pk_add_f32 v[4:5], v[4:5], v[20:21]
	v_pk_add_f32 v[2:3], v[2:3], v[18:19]
	v_pk_add_f32 v[4:5], v[4:5], v[24:25]
	v_pk_add_f32 v[2:3], v[2:3], v[22:23]
	v_pk_add_f32 v[4:5], v[4:5], v[28:29]
	v_pk_add_f32 v[2:3], v[2:3], v[26:27]
	v_pk_add_f32 v[4:5], v[4:5], v[32:33]
	v_pk_add_f32 v[2:3], v[2:3], v[30:31]
	v_lshlrev_b64 v[40:41], 11, v[40:41]
	v_lshl_add_u64 v[40:41], s[10:11], 0, v[40:41]
	v_lshl_add_u64 v[40:41], v[40:41], 0, v[34:35]
	s_waitcnt vmcnt(2)
	v_add_f32_e32 v2, v2, v36
	v_add_f32_e32 v3, v3, v37
	v_add_f32_e32 v4, v4, v38
	v_add_f32_e32 v5, v5, v39
	v_mul_f32_e32 v2, 0xbfb8aa3b, v2
	v_mul_f32_e32 v3, 0xbfb8aa3b, v3
	v_mul_f32_e32 v4, 0xbfb8aa3b, v4
	v_mul_f32_e32 v5, 0xbfb8aa3b, v5
	v_exp_f32_e32 v2, v2
	v_exp_f32_e32 v3, v3
	v_exp_f32_e32 v4, v4
	v_exp_f32_e32 v5, v5
	v_add_f32_e32 v2, 1.0, v2
	v_add_f32_e32 v3, 1.0, v3
	v_add_f32_e32 v4, 1.0, v4
	v_add_f32_e32 v5, 1.0, v5
	v_rcp_f32_e32 v2, v2
	v_rcp_f32_e32 v3, v3
	v_rcp_f32_e32 v4, v4
	v_rcp_f32_e32 v5, v5
	s_waitcnt vmcnt(1)
	v_lshlrev_b32_e32 v1, 16, v44
	v_and_b32_e32 v7, 0xffff0000, v44
	v_lshlrev_b32_e32 v9, 16, v45
	s_waitcnt vmcnt(0)
	v_and_b32_e32 v8, 0xffff0000, v42
	v_lshlrev_b32_e32 v10, 16, v43
	v_and_b32_e32 v11, 0xffff0000, v45
	v_mul_f32_e32 v1, v2, v1
	v_mul_f32_e32 v2, v3, v7
	v_mul_f32_e32 v3, v4, v9
	v_lshlrev_b32_e32 v6, 16, v42
	v_and_b32_e32 v12, 0xffff0000, v43
	v_mul_f32_e32 v4, v5, v11
	v_mul_f32_e32 v2, v2, v8
	v_mul_f32_e32 v3, v3, v10
	v_mul_f32_e32 v1, v1, v6
	v_mul_f32_e32 v4, v4, v12
	v_cvt_pk_bf16_f32 v2, v1, v2
	v_cvt_pk_bf16_f32 v3, v3, v4
	global_store_dwordx2 v[40:41], v[2:3], off offset:1024
	s_cbranch_scc1 .LBB0_1165

.LBB0_1187:
	s_and_b32 s23, s2, 7
	s_lshl_b32 s16, s23, 16
	s_add_u32 s24, s44, s16
	v_mov_b32_e32 v1, v228
	s_addc_u32 s25, s45, 0
	s_and_b32 s16, s19, 0xffffffe0
	s_ashr_i32 s17, s16, 31
	v_and_b32_e32 v72, 31, v1
	v_ashrrev_i32_e32 v73, 5, v1
	s_lshl_b64 s[26:27], s[16:17], 10
	s_add_u32 s26, s8, s26
	s_addc_u32 s27, s9, s27
	s_barrier
	s_mov_b32 s101, m0
	s_mul_i32 s100, s18, 0x180
	v_lshrrev_b32_e32 v24, 2, v1
	v_bfe_u32 v25, v1, 4, 2
	v_lshlrev_b32_e32 v24, 10, v24
	v_xor_b32_e32 v25, v25, v1
	v_bfe_u32 v26, v72, 2, 2
	v_and_b32_e32 v25, 3, v25
	v_xor_b32_e32 v26, v26, v73
	v_lshl_or_b32 v24, v25, 4, v24
	v_lshlrev_b32_e32 v26, 4, v26
	v_lshl_or_b32 v25, v72, 6, v26
	v_add_u32_e32 v25, s100, v25
	v_xor_b32_e32 v26, 32, v25
	s_add_u32 s98, s24, s4
	s_addc_u32 s99, s25, 0
	s_add_i32 m0, s100, 0x0
	s_nop 0
	global_load_lds_dwordx4 v24, s[98:99]
	s_add_u32 s98, s24, s4
	s_addc_u32 s99, s25, 0
	s_add_u32 s98, s98, 0x4000
	s_addc_u32 s99, s99, 0
	s_add_i32 m0, s100, 0x400
	s_nop 0
	global_load_lds_dwordx4 v24, s[98:99]
	s_add_u32 s98, s24, s4
	s_addc_u32 s99, s25, 0
	s_add_u32 s98, s98, 0x8000
	s_addc_u32 s99, s99, 0
	s_add_i32 m0, s100, 0x800
	s_nop 0
	global_load_lds_dwordx4 v24, s[98:99]
	s_add_u32 s98, s24, s4
	s_addc_u32 s99, s25, 0
	s_add_u32 s98, s98, 0xc000
	s_addc_u32 s99, s99, 0
	s_add_i32 m0, s100, 0xc00
	s_nop 0
	global_load_lds_dwordx4 v24, s[98:99]
	s_add_u32 s98, s26, s4
	s_addc_u32 s99, s27, 0
	s_add_u32 s98, s98, 0x1000000
	s_addc_u32 s99, s99, 0
	s_add_i32 m0, s100, 0x1000
	s_nop 0
	global_load_lds_dwordx4 v24, s[98:99]
	s_add_u32 s98, s26, s4
	s_addc_u32 s99, s27, 0
	s_add_u32 s98, s98, 0x1004000
	s_addc_u32 s99, s99, 0
	s_add_i32 m0, s100, 0x1400
	s_nop 0
	global_load_lds_dwordx4 v24, s[98:99]
	s_add_u32 s98, s24, s4
	s_addc_u32 s99, s25, 0
	s_add_u32 s98, s98, 0x40
	s_addc_u32 s99, s99, 0
	s_add_i32 m0, s100, 0x1800
	s_nop 0
	global_load_lds_dwordx4 v24, s[98:99]
	s_add_u32 s98, s24, s4
	s_addc_u32 s99, s25, 0
	s_add_u32 s98, s98, 0x4040
	s_addc_u32 s99, s99, 0
	s_add_i32 m0, s100, 0x1c00
	s_nop 0
	global_load_lds_dwordx4 v24, s[98:99]
	s_add_u32 s98, s24, s4
	s_addc_u32 s99, s25, 0
	s_add_u32 s98, s98, 0x8040
	s_addc_u32 s99, s99, 0
	s_add_i32 m0, s100, 0x2000
	s_nop 0
	global_load_lds_dwordx4 v24, s[98:99]
	s_add_u32 s98, s24, s4
	s_addc_u32 s99, s25, 0
	s_add_u32 s98, s98, 0xc040
	s_addc_u32 s99, s99, 0
	s_add_i32 m0, s100, 0x2400
	s_nop 0
	global_load_lds_dwordx4 v24, s[98:99]
	s_add_u32 s98, s26, s4
	s_addc_u32 s99, s27, 0
	s_add_u32 s98, s98, 0x1000040
	s_addc_u32 s99, s99, 0
	s_add_i32 m0, s100, 0x2800
	s_nop 0
	global_load_lds_dwordx4 v24, s[98:99]
	s_add_u32 s98, s26, s4
	s_addc_u32 s99, s27, 0
	s_add_u32 s98, s98, 0x1004040
	s_addc_u32 s99, s99, 0
	s_add_i32 m0, s100, 0x2c00
	s_nop 0
	global_load_lds_dwordx4 v24, s[98:99]
	s_waitcnt vmcnt(6)
	ds_read_b128 v[10:13], v25
	ds_read_b128 v[2:5], v25 offset:2048
	ds_read_b128 v[6:9], v25 offset:4096
	ds_read_b128 v[36:39], v26
	ds_read_b128 v[40:43], v26 offset:2048
	ds_read_b128 v[56:59], v26 offset:4096
	s_waitcnt vmcnt(0)
	ds_read_b128 v[48:51], v25 offset:6144
	ds_read_b128 v[44:47], v25 offset:8192
	ds_read_b128 v[64:67], v25 offset:10240
	ds_read_b128 v[52:55], v26 offset:6144
	ds_read_b128 v[60:63], v26 offset:8192
	ds_read_b128 v[68:71], v26 offset:10240
	s_mov_b32 m0, s101
	s_waitcnt lgkmcnt(0)
	v_mfma_f32_32x32x16_bf16 v[18:33], v[10:13], v[6:9], 0
	v_or_b32_e32 v34, s18, v72
	v_mul_lo_u32 v34, v34, s22
	s_add_u32 s16, s16, 0x4000
	s_addc_u32 s17, s17, 0
	s_add_i32 s2, s2, s46
	s_add_i32 s19, s19, s20
	s_cmpk_lt_i32 s2, 0x80
	v_mfma_f32_32x32x16_bf16 v[2:17], v[2:5], v[6:9], 0
	v_mfma_f32_32x32x16_bf16 v[18:33], v[36:39], v[56:59], v[18:33]
	v_lshlrev_b32_e32 v36, 4, v73
	v_add3_u32 v34, 0, v34, v36
	v_mfma_f32_32x32x16_bf16 v[2:17], v[40:43], v[56:59], v[2:17]
	v_mfma_f32_32x32x16_bf16 v[18:33], v[48:51], v[64:67], v[18:33]
	v_mfma_f32_32x32x16_bf16 v[2:17], v[44:47], v[64:67], v[2:17]
	v_mfma_f32_32x32x16_bf16 v[18:33], v[52:55], v[68:71], v[18:33]
	v_mfma_f32_32x32x16_bf16 v[2:17], v[60:63], v[68:71], v[2:17]
	s_nop 10
	s_barrier
	ds_write_b128 v34, v[18:21]
	ds_write_b128 v34, v[2:5] offset:128
	ds_write_b128 v34, v[22:25] offset:32
	ds_write_b128 v34, v[6:9] offset:160
	ds_write_b128 v34, v[26:29] offset:64
	ds_write_b128 v34, v[10:13] offset:192
	ds_write_b128 v34, v[30:33] offset:96
	ds_write_b128 v34, v[14:17] offset:224
	v_add_u32_e32 v2, s0, v1
	v_lshlrev_b32_e32 v1, 2, v1
	v_ashrrev_i32_e32 v36, 4, v2
	v_and_b32_e32 v1, 60, v1
	v_lshlrev_b32_e32 v2, 2, v1
	v_mul_lo_u32 v3, v36, s22
	v_lshl_or_b32 v1, s23, 6, v1
	v_add3_u32 v30, 0, v2, v3
	v_ashrrev_i32_e32 v37, 31, v36
	v_lshlrev_b32_e32 v34, 2, v1
	s_waitcnt lgkmcnt(0)
	s_barrier
	ds_read_b128 v[2:5], v30
	ds_read_b128 v[6:9], v30 offset:8704
	ds_read_b128 v[10:13], v30 offset:17408
	ds_read_b128 v[14:17], v30 offset:26112
	ds_read_b128 v[18:21], v30 offset:34816
	ds_read_b128 v[22:25], v30 offset:43520
	ds_read_b128 v[26:29], v30 offset:52224
	ds_read_b128 v[30:33], v30 offset:60928
	s_waitcnt lgkmcnt(0)
	s_barrier
	v_lshl_add_u64 v[40:41], s[16:17], 0, v[36:37]
	global_load_dwordx4 v[36:39], v34, s[56:57]
	v_lshlrev_b64 v[42:43], 10, v[40:41]
	v_lshl_add_u64 v[44:45], s[8:9], 0, v[42:43]
	v_lshlrev_b32_e32 v34, 1, v1
	v_lshl_add_u64 v[44:45], v[44:45], 0, v[34:35]
	v_lshl_add_u64 v[42:43], s[6:7], 0, v[42:43]
	global_load_dwordx2 v[44:45], v[44:45], off
	v_lshl_add_u64 v[42:43], v[42:43], 0, v[34:35]
	global_load_dwordx2 v[42:43], v[42:43], off
	v_pk_add_f32 v[4:5], v[4:5], 0 op_sel_hi:[1,0]
	v_pk_add_f32 v[2:3], v[2:3], 0 op_sel_hi:[1,0]
	v_pk_add_f32 v[4:5], v[4:5], v[8:9]
	v_pk_add_f32 v[2:3], v[2:3], v[6:7]
	v_pk_add_f32 v[4:5], v[4:5], v[12:13]
	v_pk_add_f32 v[2:3], v[2:3], v[10:11]
	v_pk_add_f32 v[4:5], v[4:5], v[16:17]
	v_pk_add_f32 v[2:3], v[2:3], v[14:15]
	v_pk_add_f32 v[4:5], v[4:5], v[20:21]
	v_pk_add_f32 v[2:3], v[2:3], v[18:19]
	v_pk_add_f32 v[4:5], v[4:5], v[24:25]
	v_pk_add_f32 v[2:3], v[2:3], v[22:23]
	v_pk_add_f32 v[4:5], v[4:5], v[28:29]
	v_pk_add_f32 v[2:3], v[2:3], v[26:27]
	v_pk_add_f32 v[4:5], v[4:5], v[32:33]
	v_pk_add_f32 v[2:3], v[2:3], v[30:31]
	v_lshlrev_b64 v[40:41], 11, v[40:41]
	v_lshl_add_u64 v[40:41], s[10:11], 0, v[40:41]
	v_lshl_add_u64 v[40:41], v[40:41], 0, v[34:35]
	s_waitcnt vmcnt(2)
	v_add_f32_e32 v2, v2, v36
	v_add_f32_e32 v3, v3, v37
	v_add_f32_e32 v4, v4, v38
	v_add_f32_e32 v5, v5, v39
	v_mul_f32_e32 v2, 0xbfb8aa3b, v2
	v_mul_f32_e32 v3, 0xbfb8aa3b, v3
	v_mul_f32_e32 v4, 0xbfb8aa3b, v4
	v_mul_f32_e32 v5, 0xbfb8aa3b, v5
	v_exp_f32_e32 v2, v2
	v_exp_f32_e32 v3, v3
	v_exp_f32_e32 v4, v4
	v_exp_f32_e32 v5, v5
	v_add_f32_e32 v2, 1.0, v2
	v_add_f32_e32 v3, 1.0, v3
	v_add_f32_e32 v4, 1.0, v4
	v_add_f32_e32 v5, 1.0, v5
	v_rcp_f32_e32 v2, v2
	v_rcp_f32_e32 v3, v3
	v_rcp_f32_e32 v4, v4
	v_rcp_f32_e32 v5, v5
	s_waitcnt vmcnt(1)
	v_lshlrev_b32_e32 v1, 16, v44
	v_and_b32_e32 v7, 0xffff0000, v44
	v_lshlrev_b32_e32 v9, 16, v45
	s_waitcnt vmcnt(0)
	v_and_b32_e32 v8, 0xffff0000, v42
	v_lshlrev_b32_e32 v10, 16, v43
	v_and_b32_e32 v11, 0xffff0000, v45
	v_mul_f32_e32 v1, v2, v1
	v_mul_f32_e32 v2, v3, v7
	v_mul_f32_e32 v3, v4, v9
	v_lshlrev_b32_e32 v6, 16, v42
	v_and_b32_e32 v12, 0xffff0000, v43
	v_mul_f32_e32 v4, v5, v11
	v_mul_f32_e32 v2, v2, v8
	v_mul_f32_e32 v3, v3, v10
	v_mul_f32_e32 v1, v1, v6
	v_mul_f32_e32 v4, v4, v12
	v_cvt_pk_bf16_f32 v2, v1, v2
	v_cvt_pk_bf16_f32 v3, v3, v4
	global_store_dwordx2 v[40:41], v[2:3], off offset:1024
	s_cbranch_scc1 .LBB0_1187

.LBB0_1244:
	s_and_b32 s19, s18, 15
	s_ashr_i32 s12, s18, 4
	s_lshl_b32 s13, s19, 17
	s_add_u32 s20, s44, s13
	v_mov_b32_e32 v1, v228
	s_addc_u32 s21, s45, 0
	s_lshl_b32 s22, s12, 5
	s_ashr_i32 s23, s22, 31
	v_and_b32_e32 v120, 31, v1
	v_ashrrev_i32_e32 v121, 5, v1
	s_lshl_b64 s[22:23], s[22:23], 11
	s_add_u32 s22, s46, s22
	s_addc_u32 s23, s47, s23
	s_barrier
	s_mov_b32 s101, m0
	s_mul_i32 s100, s2, 0x180
	v_lshrrev_b32_e32 v24, 2, v1
	v_bfe_u32 v25, v1, 4, 2
	v_lshlrev_b32_e32 v24, 11, v24
	v_xor_b32_e32 v25, v25, v1
	v_bfe_u32 v26, v120, 2, 2
	v_and_b32_e32 v25, 3, v25
	v_xor_b32_e32 v26, v26, v121
	v_lshl_or_b32 v24, v25, 4, v24
	v_lshlrev_b32_e32 v26, 4, v26
	v_lshl_or_b32 v25, v120, 6, v26
	v_add_u32_e32 v25, s100, v25
	v_xor_b32_e32 v26, 32, v25
	s_add_u32 s98, s20, s4
	s_addc_u32 s99, s21, 0
	s_add_i32 m0, s100, 0x0
	s_nop 0
	global_load_lds_dwordx4 v24, s[98:99]
	s_add_u32 s98, s20, s4
	s_addc_u32 s99, s21, 0
	s_add_u32 s98, s98, 0x8000
	s_addc_u32 s99, s99, 0
	s_add_i32 m0, s100, 0x400
	s_nop 0
	global_load_lds_dwordx4 v24, s[98:99]
	s_add_u32 s98, s20, s4
	s_addc_u32 s99, s21, 0
	s_add_u32 s98, s98, 0x10000
	s_addc_u32 s99, s99, 0
	s_add_i32 m0, s100, 0x800
	s_nop 0
	global_load_lds_dwordx4 v24, s[98:99]
	s_add_u32 s98, s20, s4
	s_addc_u32 s99, s21, 0
	s_add_u32 s98, s98, 0x18000
	s_addc_u32 s99, s99, 0
	s_add_i32 m0, s100, 0xc00
	s_nop 0
	global_load_lds_dwordx4 v24, s[98:99]
	s_add_u32 s98, s22, s4
	s_addc_u32 s99, s23, 0
	s_add_u32 s98, s98, 0x2000000
	s_addc_u32 s99, s99, 0
	s_add_i32 m0, s100, 0x1000
	s_nop 0
	global_load_lds_dwordx4 v24, s[98:99]
	s_add_u32 s98, s22, s4
	s_addc_u32 s99, s23, 0
	s_add_u32 s98, s98, 0x2008000
	s_addc_u32 s99, s99, 0
	s_add_i32 m0, s100, 0x1400
	s_nop 0
	global_load_lds_dwordx4 v24, s[98:99]
	s_add_u32 s98, s20, s4
	s_addc_u32 s99, s21, 0
	s_add_u32 s98, s98, 0x40
	s_addc_u32 s99, s99, 0
	s_add_i32 m0, s100, 0x1800
	s_nop 0
	global_load_lds_dwordx4 v24, s[98:99]
	s_add_u32 s98, s20, s4
	s_addc_u32 s99, s21, 0
	s_add_u32 s98, s98, 0x8040
	s_addc_u32 s99, s99, 0
	s_add_i32 m0, s100, 0x1c00
	s_nop 0
	global_load_lds_dwordx4 v24, s[98:99]
	s_add_u32 s98, s20, s4
	s_addc_u32 s99, s21, 0
	s_add_u32 s98, s98, 0x10040
	s_addc_u32 s99, s99, 0
	s_add_i32 m0, s100, 0x2000
	s_nop 0
	global_load_lds_dwordx4 v24, s[98:99]
	s_add_u32 s98, s20, s4
	s_addc_u32 s99, s21, 0
	s_add_u32 s98, s98, 0x18040
	s_addc_u32 s99, s99, 0
	s_add_i32 m0, s100, 0x2400
	s_nop 0
	global_load_lds_dwordx4 v24, s[98:99]
	s_add_u32 s98, s22, s4
	s_addc_u32 s99, s23, 0
	s_add_u32 s98, s98, 0x2000040
	s_addc_u32 s99, s99, 0
	s_add_i32 m0, s100, 0x2800
	s_nop 0
	global_load_lds_dwordx4 v24, s[98:99]
	s_add_u32 s98, s22, s4
	s_addc_u32 s99, s23, 0
	s_add_u32 s98, s98, 0x2008040
	s_addc_u32 s99, s99, 0
	s_add_i32 m0, s100, 0x2c00
	s_nop 0
	global_load_lds_dwordx4 v24, s[98:99]
	s_waitcnt vmcnt(6)
	ds_read_b128 v[10:13], v25
	ds_read_b128 v[2:5], v25 offset:2048
	ds_read_b128 v[6:9], v25 offset:4096
	ds_read_b128 v[36:39], v26
	ds_read_b128 v[40:43], v26 offset:2048
	ds_read_b128 v[104:107], v26 offset:4096
	s_waitcnt lgkmcnt(0)
	s_add_u32 s98, s20, s4
	s_addc_u32 s99, s21, 0
	s_add_u32 s98, s98, 0x80
	s_addc_u32 s99, s99, 0
	s_add_i32 m0, s100, 0x0
	s_nop 0
	global_load_lds_dwordx4 v24, s[98:99]
	s_add_u32 s98, s20, s4
	s_addc_u32 s99, s21, 0
	s_add_u32 s98, s98, 0x8080
	s_addc_u32 s99, s99, 0
	s_add_i32 m0, s100, 0x400
	s_nop 0
	global_load_lds_dwordx4 v24, s[98:99]
	s_add_u32 s98, s20, s4
	s_addc_u32 s99, s21, 0
	s_add_u32 s98, s98, 0x10080
	s_addc_u32 s99, s99, 0
	s_add_i32 m0, s100, 0x800
	s_nop 0
	global_load_lds_dwordx4 v24, s[98:99]
	s_add_u32 s98, s20, s4
	s_addc_u32 s99, s21, 0
	s_add_u32 s98, s98, 0x18080
	s_addc_u32 s99, s99, 0
	s_add_i32 m0, s100, 0xc00
	s_nop 0
	global_load_lds_dwordx4 v24, s[98:99]
	s_add_u32 s98, s22, s4
	s_addc_u32 s99, s23, 0
	s_add_u32 s98, s98, 0x2000080
	s_addc_u32 s99, s99, 0
	s_add_i32 m0, s100, 0x1000
	s_nop 0
	global_load_lds_dwordx4 v24, s[98:99]
	s_add_u32 s98, s22, s4
	s_addc_u32 s99, s23, 0
	s_add_u32 s98, s98, 0x2008080
	s_addc_u32 s99, s99, 0
	s_add_i32 m0, s100, 0x1400
	s_nop 0
	global_load_lds_dwordx4 v24, s[98:99]
	s_waitcnt vmcnt(6)
	ds_read_b128 v[48:51], v25 offset:6144
	ds_read_b128 v[44:47], v25 offset:8192
	ds_read_b128 v[56:59], v25 offset:10240
	ds_read_b128 v[52:55], v26 offset:6144
	ds_read_b128 v[64:67], v26 offset:8192
	ds_read_b128 v[60:63], v26 offset:10240
	s_waitcnt lgkmcnt(0)
	s_add_u32 s98, s20, s4
	s_addc_u32 s99, s21, 0
	s_add_u32 s98, s98, 0xc0
	s_addc_u32 s99, s99, 0
	s_add_i32 m0, s100, 0x1800
	s_nop 0
	global_load_lds_dwordx4 v24, s[98:99]
	s_add_u32 s98, s20, s4
	s_addc_u32 s99, s21, 0
	s_add_u32 s98, s98, 0x80c0
	s_addc_u32 s99, s99, 0
	s_add_i32 m0, s100, 0x1c00
	s_nop 0
	global_load_lds_dwordx4 v24, s[98:99]
	s_add_u32 s98, s20, s4
	s_addc_u32 s99, s21, 0
	s_add_u32 s98, s98, 0x100c0
	s_addc_u32 s99, s99, 0
	s_add_i32 m0, s100, 0x2000
	s_nop 0
	global_load_lds_dwordx4 v24, s[98:99]
	s_add_u32 s98, s20, s4
	s_addc_u32 s99, s21, 0
	s_add_u32 s98, s98, 0x180c0
	s_addc_u32 s99, s99, 0
	s_add_i32 m0, s100, 0x2400
	s_nop 0
	global_load_lds_dwordx4 v24, s[98:99]
	s_add_u32 s98, s22, s4
	s_addc_u32 s99, s23, 0
	s_add_u32 s98, s98, 0x20000c0
	s_addc_u32 s99, s99, 0
	s_add_i32 m0, s100, 0x2800
	s_nop 0
	global_load_lds_dwordx4 v24, s[98:99]
	s_add_u32 s98, s22, s4
	s_addc_u32 s99, s23, 0
	s_add_u32 s98, s98, 0x20080c0
	s_addc_u32 s99, s99, 0
	s_add_i32 m0, s100, 0x2c00
	s_nop 0
	global_load_lds_dwordx4 v24, s[98:99]
	s_waitcnt vmcnt(6)
	ds_read_b128 v[72:75], v25
	ds_read_b128 v[68:71], v25 offset:2048
	ds_read_b128 v[80:83], v25 offset:4096
	ds_read_b128 v[76:79], v26
	ds_read_b128 v[88:91], v26 offset:2048
	ds_read_b128 v[84:87], v26 offset:4096
	s_waitcnt vmcnt(0)
	ds_read_b128 v[96:99], v25 offset:6144
	ds_read_b128 v[92:95], v25 offset:8192
	ds_read_b128 v[112:115], v25 offset:10240
	ds_read_b128 v[100:103], v26 offset:6144
	ds_read_b128 v[108:111], v26 offset:8192
	ds_read_b128 v[116:119], v26 offset:10240
	s_mov_b32 m0, s101
	s_waitcnt lgkmcnt(0)
	v_mfma_f32_32x32x16_bf16 v[18:33], v[10:13], v[6:9], 0
	v_or_b32_e32 v34, s2, v120
	v_mul_lo_u32 v34, v34, s17
	s_and_b64 vcc, exec, s[0:1]
	v_mfma_f32_32x32x16_bf16 v[2:17], v[2:5], v[6:9], 0
	v_mfma_f32_32x32x16_bf16 v[18:33], v[36:39], v[104:107], v[18:33]
	v_lshlrev_b32_e32 v36, 4, v121
	v_add3_u32 v34, 0, v34, v36
	v_mfma_f32_32x32x16_bf16 v[2:17], v[40:43], v[104:107], v[2:17]
	v_mfma_f32_32x32x16_bf16 v[18:33], v[48:51], v[56:59], v[18:33]
	v_mfma_f32_32x32x16_bf16 v[2:17], v[44:47], v[56:59], v[2:17]
	v_mfma_f32_32x32x16_bf16 v[18:33], v[52:55], v[60:63], v[18:33]
	v_mfma_f32_32x32x16_bf16 v[2:17], v[64:67], v[60:63], v[2:17]
	v_mfma_f32_32x32x16_bf16 v[18:33], v[72:75], v[80:83], v[18:33]
	v_mfma_f32_32x32x16_bf16 v[2:17], v[68:71], v[80:83], v[2:17]
	v_mfma_f32_32x32x16_bf16 v[18:33], v[76:79], v[84:87], v[18:33]
	v_mfma_f32_32x32x16_bf16 v[2:17], v[88:91], v[84:87], v[2:17]
	v_mfma_f32_32x32x16_bf16 v[18:33], v[96:99], v[112:115], v[18:33]
	v_mfma_f32_32x32x16_bf16 v[2:17], v[92:95], v[112:115], v[2:17]
	v_mfma_f32_32x32x16_bf16 v[18:33], v[100:103], v[116:119], v[18:33]
	v_mfma_f32_32x32x16_bf16 v[2:17], v[108:111], v[116:119], v[2:17]
	s_nop 10
	s_barrier
	ds_write_b128 v34, v[18:21]
	ds_write_b128 v34, v[2:5] offset:128
	ds_write_b128 v34, v[22:25] offset:32
	ds_write_b128 v34, v[6:9] offset:160
	ds_write_b128 v34, v[26:29] offset:64
	ds_write_b128 v34, v[10:13] offset:192
	ds_write_b128 v34, v[30:33] offset:96
	ds_write_b128 v34, v[14:17] offset:224
	v_add_u32_e32 v2, s14, v1
	v_lshlrev_b32_e32 v1, 2, v1
	v_ashrrev_i32_e32 v36, 4, v2
	v_and_b32_e32 v1, 60, v1
	v_lshlrev_b32_e32 v1, 2, v1
	v_mul_lo_u32 v2, v36, s17
	v_add3_u32 v2, 0, v1, v2
	s_waitcnt lgkmcnt(0)
	s_barrier
	ds_read_b128 v[30:33], v2
	ds_read_b128 v[26:29], v2 offset:8704
	ds_read_b128 v[22:25], v2 offset:17408
	ds_read_b128 v[18:21], v2 offset:26112
	ds_read_b128 v[14:17], v2 offset:34816
	ds_read_b128 v[10:13], v2 offset:43520
	ds_read_b128 v[6:9], v2 offset:52224
	ds_read_b128 v[2:5], v2 offset:60928
	s_waitcnt lgkmcnt(0)
	s_barrier
	s_cbranch_vccnz .LBB0_1243
	s_ashr_i32 s13, s12, 31
	v_ashrrev_i32_e32 v37, 31, v36
	s_lshl_b64 s[12:13], s[12:13], 15
	v_lshlrev_b64 v[36:37], 10, v[36:37]
	v_lshl_add_u64 v[36:37], v[36:37], 0, s[12:13]
	v_lshlrev_b64 v[40:41], 2, v[36:37]
	v_lshl_add_u64 v[36:37], s[42:43], 0, v[40:41]
	v_lshl_or_b32 v34, s19, 8, v1
	v_lshl_add_u64 v[36:37], v[36:37], 0, v[34:35]
	global_load_dwordx4 v[36:39], v[36:37], off
	v_pk_add_f32 v[32:33], v[32:33], 0 op_sel_hi:[1,0]
	v_pk_add_f32 v[30:31], v[30:31], 0 op_sel_hi:[1,0]
	v_pk_add_f32 v[28:29], v[32:33], v[28:29]
	v_pk_add_f32 v[26:27], v[30:31], v[26:27]
	v_pk_add_f32 v[24:25], v[28:29], v[24:25]
	v_pk_add_f32 v[22:23], v[26:27], v[22:23]
	v_pk_add_f32 v[20:21], v[24:25], v[20:21]
	v_pk_add_f32 v[18:19], v[22:23], v[18:19]
	v_pk_add_f32 v[16:17], v[20:21], v[16:17]
	v_pk_add_f32 v[14:15], v[18:19], v[14:15]
	v_pk_add_f32 v[12:13], v[16:17], v[12:13]
	v_pk_add_f32 v[10:11], v[14:15], v[10:11]
	v_pk_add_f32 v[8:9], v[12:13], v[8:9]
	v_pk_add_f32 v[6:7], v[10:11], v[6:7]
	v_lshl_add_u64 v[18:19], s[6:7], 0, v[40:41]
	v_pk_add_f32 v[4:5], v[8:9], v[4:5]
	v_pk_add_f32 v[2:3], v[6:7], v[2:3]
	v_lshl_add_u64 v[6:7], v[18:19], 0, v[34:35]
	s_waitcnt vmcnt(0)
	v_pk_add_f32 v[4:5], v[4:5], v[38:39]
	v_pk_add_f32 v[2:3], v[2:3], v[36:37]
	global_store_dwordx4 v[6:7], v[2:5], off
	s_branch .LBB0_1243

.LBB0_1276:
	s_and_b32 s17, s88, 15
	s_ashr_i32 s10, s88, 4
	s_lshl_b32 s11, s17, 17
	s_add_u32 s18, s44, s11
	v_mov_b32_e32 v118, v228
	s_addc_u32 s19, s45, 0
	s_lshl_b32 s20, s10, 5
	s_ashr_i32 s21, s20, 31
	v_and_b32_e32 v119, 31, v118
	v_ashrrev_i32_e32 v120, 5, v118
	s_lshl_b64 s[20:21], s[20:21], 11
	s_add_u32 s20, s46, s20
	s_addc_u32 s21, s47, s21
	s_barrier
	s_mov_b32 s101, m0
	s_mul_i32 s100, s12, 0x180
	v_lshrrev_b32_e32 v22, 2, v118
	v_bfe_u32 v23, v118, 4, 2
	v_lshlrev_b32_e32 v22, 11, v22
	v_xor_b32_e32 v23, v23, v118
	v_bfe_u32 v24, v119, 2, 2
	v_and_b32_e32 v23, 3, v23
	v_xor_b32_e32 v24, v24, v120
	v_lshl_or_b32 v22, v23, 4, v22
	v_lshlrev_b32_e32 v24, 4, v24
	v_lshl_or_b32 v23, v119, 6, v24
	v_add_u32_e32 v23, s100, v23
	v_xor_b32_e32 v24, 32, v23
	s_add_u32 s98, s18, s2
	s_addc_u32 s99, s19, 0
	s_add_i32 m0, s100, 0x0
	s_nop 0
	global_load_lds_dwordx4 v22, s[98:99]
	s_add_u32 s98, s18, s2
	s_addc_u32 s99, s19, 0
	s_add_u32 s98, s98, 0x8000
	s_addc_u32 s99, s99, 0
	s_add_i32 m0, s100, 0x400
	s_nop 0
	global_load_lds_dwordx4 v22, s[98:99]
	s_add_u32 s98, s18, s2
	s_addc_u32 s99, s19, 0
	s_add_u32 s98, s98, 0x10000
	s_addc_u32 s99, s99, 0
	s_add_i32 m0, s100, 0x800
	s_nop 0
	global_load_lds_dwordx4 v22, s[98:99]
	s_add_u32 s98, s18, s2
	s_addc_u32 s99, s19, 0
	s_add_u32 s98, s98, 0x18000
	s_addc_u32 s99, s99, 0
	s_add_i32 m0, s100, 0xc00
	s_nop 0
	global_load_lds_dwordx4 v22, s[98:99]
	s_add_u32 s98, s20, s2
	s_addc_u32 s99, s21, 0
	s_add_u32 s98, s98, 0x2000000
	s_addc_u32 s99, s99, 0
	s_add_i32 m0, s100, 0x1000
	s_nop 0
	global_load_lds_dwordx4 v22, s[98:99]
	s_add_u32 s98, s20, s2
	s_addc_u32 s99, s21, 0
	s_add_u32 s98, s98, 0x2008000
	s_addc_u32 s99, s99, 0
	s_add_i32 m0, s100, 0x1400
	s_nop 0
	global_load_lds_dwordx4 v22, s[98:99]
	s_add_u32 s98, s18, s2
	s_addc_u32 s99, s19, 0
	s_add_u32 s98, s98, 0x40
	s_addc_u32 s99, s99, 0
	s_add_i32 m0, s100, 0x1800
	s_nop 0
	global_load_lds_dwordx4 v22, s[98:99]
	s_add_u32 s98, s18, s2
	s_addc_u32 s99, s19, 0
	s_add_u32 s98, s98, 0x8040
	s_addc_u32 s99, s99, 0
	s_add_i32 m0, s100, 0x1c00
	s_nop 0
	global_load_lds_dwordx4 v22, s[98:99]
	s_add_u32 s98, s18, s2
	s_addc_u32 s99, s19, 0
	s_add_u32 s98, s98, 0x10040
	s_addc_u32 s99, s99, 0
	s_add_i32 m0, s100, 0x2000
	s_nop 0
	global_load_lds_dwordx4 v22, s[98:99]
	s_add_u32 s98, s18, s2
	s_addc_u32 s99, s19, 0
	s_add_u32 s98, s98, 0x18040
	s_addc_u32 s99, s99, 0
	s_add_i32 m0, s100, 0x2400
	s_nop 0
	global_load_lds_dwordx4 v22, s[98:99]
	s_add_u32 s98, s20, s2
	s_addc_u32 s99, s21, 0
	s_add_u32 s98, s98, 0x2000040
	s_addc_u32 s99, s99, 0
	s_add_i32 m0, s100, 0x2800
	s_nop 0
	global_load_lds_dwordx4 v22, s[98:99]
	s_add_u32 s98, s20, s2
	s_addc_u32 s99, s21, 0
	s_add_u32 s98, s98, 0x2008040
	s_addc_u32 s99, s99, 0
	s_add_i32 m0, s100, 0x2c00
	s_nop 0
	global_load_lds_dwordx4 v22, s[98:99]
	s_waitcnt vmcnt(6)
	ds_read_b128 v[8:11], v23
	ds_read_b128 v[0:3], v23 offset:2048
	ds_read_b128 v[4:7], v23 offset:4096
	ds_read_b128 v[34:37], v24
	ds_read_b128 v[38:41], v24 offset:2048
	ds_read_b128 v[102:105], v24 offset:4096
	s_waitcnt lgkmcnt(0)
	s_add_u32 s98, s18, s2
	s_addc_u32 s99, s19, 0
	s_add_u32 s98, s98, 0x80
	s_addc_u32 s99, s99, 0
	s_add_i32 m0, s100, 0x0
	s_nop 0
	global_load_lds_dwordx4 v22, s[98:99]
	s_add_u32 s98, s18, s2
	s_addc_u32 s99, s19, 0
	s_add_u32 s98, s98, 0x8080
	s_addc_u32 s99, s99, 0
	s_add_i32 m0, s100, 0x400
	s_nop 0
	global_load_lds_dwordx4 v22, s[98:99]
	s_add_u32 s98, s18, s2
	s_addc_u32 s99, s19, 0
	s_add_u32 s98, s98, 0x10080
	s_addc_u32 s99, s99, 0
	s_add_i32 m0, s100, 0x800
	s_nop 0
	global_load_lds_dwordx4 v22, s[98:99]
	s_add_u32 s98, s18, s2
	s_addc_u32 s99, s19, 0
	s_add_u32 s98, s98, 0x18080
	s_addc_u32 s99, s99, 0
	s_add_i32 m0, s100, 0xc00
	s_nop 0
	global_load_lds_dwordx4 v22, s[98:99]
	s_add_u32 s98, s20, s2
	s_addc_u32 s99, s21, 0
	s_add_u32 s98, s98, 0x2000080
	s_addc_u32 s99, s99, 0
	s_add_i32 m0, s100, 0x1000
	s_nop 0
	global_load_lds_dwordx4 v22, s[98:99]
	s_add_u32 s98, s20, s2
	s_addc_u32 s99, s21, 0
	s_add_u32 s98, s98, 0x2008080
	s_addc_u32 s99, s99, 0
	s_add_i32 m0, s100, 0x1400
	s_nop 0
	global_load_lds_dwordx4 v22, s[98:99]
	s_waitcnt vmcnt(6)
	ds_read_b128 v[46:49], v23 offset:6144
	ds_read_b128 v[42:45], v23 offset:8192
	ds_read_b128 v[54:57], v23 offset:10240
	ds_read_b128 v[50:53], v24 offset:6144
	ds_read_b128 v[62:65], v24 offset:8192
	ds_read_b128 v[58:61], v24 offset:10240
	s_waitcnt lgkmcnt(0)
	s_add_u32 s98, s18, s2
	s_addc_u32 s99, s19, 0
	s_add_u32 s98, s98, 0xc0
	s_addc_u32 s99, s99, 0
	s_add_i32 m0, s100, 0x1800
	s_nop 0
	global_load_lds_dwordx4 v22, s[98:99]
	s_add_u32 s98, s18, s2
	s_addc_u32 s99, s19, 0
	s_add_u32 s98, s98, 0x80c0
	s_addc_u32 s99, s99, 0
	s_add_i32 m0, s100, 0x1c00
	s_nop 0
	global_load_lds_dwordx4 v22, s[98:99]
	s_add_u32 s98, s18, s2
	s_addc_u32 s99, s19, 0
	s_add_u32 s98, s98, 0x100c0
	s_addc_u32 s99, s99, 0
	s_add_i32 m0, s100, 0x2000
	s_nop 0
	global_load_lds_dwordx4 v22, s[98:99]
	s_add_u32 s98, s18, s2
	s_addc_u32 s99, s19, 0
	s_add_u32 s98, s98, 0x180c0
	s_addc_u32 s99, s99, 0
	s_add_i32 m0, s100, 0x2400
	s_nop 0
	global_load_lds_dwordx4 v22, s[98:99]
	s_add_u32 s98, s20, s2
	s_addc_u32 s99, s21, 0
	s_add_u32 s98, s98, 0x20000c0
	s_addc_u32 s99, s99, 0
	s_add_i32 m0, s100, 0x2800
	s_nop 0
	global_load_lds_dwordx4 v22, s[98:99]
	s_add_u32 s98, s20, s2
	s_addc_u32 s99, s21, 0
	s_add_u32 s98, s98, 0x20080c0
	s_addc_u32 s99, s99, 0
	s_add_i32 m0, s100, 0x2c00
	s_nop 0
	global_load_lds_dwordx4 v22, s[98:99]
	s_waitcnt vmcnt(6)
	ds_read_b128 v[70:73], v23
	ds_read_b128 v[66:69], v23 offset:2048
	ds_read_b128 v[78:81], v23 offset:4096
	ds_read_b128 v[74:77], v24
	ds_read_b128 v[86:89], v24 offset:2048
	ds_read_b128 v[82:85], v24 offset:4096
	s_waitcnt vmcnt(0)
	ds_read_b128 v[94:97], v23 offset:6144
	ds_read_b128 v[90:93], v23 offset:8192
	ds_read_b128 v[110:113], v23 offset:10240
	ds_read_b128 v[98:101], v24 offset:6144
	ds_read_b128 v[106:109], v24 offset:8192
	ds_read_b128 v[114:117], v24 offset:10240
	s_mov_b32 m0, s101
	s_waitcnt lgkmcnt(0)
	v_mfma_f32_32x32x16_bf16 v[16:31], v[8:11], v[4:7], 0
	v_or_b32_e32 v32, s12, v119
	v_mul_lo_u32 v32, v32, s16
	s_and_b64 vcc, exec, s[0:1]
	v_mfma_f32_32x32x16_bf16 v[0:15], v[0:3], v[4:7], 0
	v_mfma_f32_32x32x16_bf16 v[16:31], v[34:37], v[102:105], v[16:31]
	v_lshlrev_b32_e32 v34, 4, v120
	v_add3_u32 v32, 0, v32, v34
	v_mfma_f32_32x32x16_bf16 v[0:15], v[38:41], v[102:105], v[0:15]
	v_mfma_f32_32x32x16_bf16 v[16:31], v[46:49], v[54:57], v[16:31]
	v_mfma_f32_32x32x16_bf16 v[0:15], v[42:45], v[54:57], v[0:15]
	v_mfma_f32_32x32x16_bf16 v[16:31], v[50:53], v[58:61], v[16:31]
	v_mfma_f32_32x32x16_bf16 v[0:15], v[62:65], v[58:61], v[0:15]
	v_mfma_f32_32x32x16_bf16 v[16:31], v[70:73], v[78:81], v[16:31]
	v_mfma_f32_32x32x16_bf16 v[0:15], v[66:69], v[78:81], v[0:15]
	v_mfma_f32_32x32x16_bf16 v[16:31], v[74:77], v[82:85], v[16:31]
	v_mfma_f32_32x32x16_bf16 v[0:15], v[86:89], v[82:85], v[0:15]
	v_mfma_f32_32x32x16_bf16 v[16:31], v[94:97], v[110:113], v[16:31]
	v_mfma_f32_32x32x16_bf16 v[0:15], v[90:93], v[110:113], v[0:15]
	v_mfma_f32_32x32x16_bf16 v[16:31], v[98:101], v[114:117], v[16:31]
	v_mfma_f32_32x32x16_bf16 v[0:15], v[106:109], v[114:117], v[0:15]
	s_nop 10
	s_barrier
	ds_write_b128 v32, v[16:19]
	ds_write_b128 v32, v[0:3] offset:128
	ds_write_b128 v32, v[20:23] offset:32
	ds_write_b128 v32, v[4:7] offset:160
	ds_write_b128 v32, v[24:27] offset:64
	ds_write_b128 v32, v[8:11] offset:192
	ds_write_b128 v32, v[28:31] offset:96
	ds_write_b128 v32, v[12:15] offset:224
	v_add_u32_e32 v0, s13, v118
	v_ashrrev_i32_e32 v34, 4, v0
	v_lshlrev_b32_e32 v0, 2, v118
	v_and_b32_e32 v0, 60, v0
	v_lshlrev_b32_e32 v32, 2, v0
	v_mul_lo_u32 v0, v34, s16
	v_add3_u32 v0, 0, v32, v0
	s_waitcnt lgkmcnt(0)
	s_barrier
	ds_read_b128 v[28:31], v0
	ds_read_b128 v[24:27], v0 offset:8704
	ds_read_b128 v[20:23], v0 offset:17408
	ds_read_b128 v[16:19], v0 offset:26112
	ds_read_b128 v[12:15], v0 offset:34816
	ds_read_b128 v[8:11], v0 offset:43520
	ds_read_b128 v[4:7], v0 offset:52224
	ds_read_b128 v[0:3], v0 offset:60928
	s_waitcnt lgkmcnt(0)
	s_barrier
	s_cbranch_vccnz .LBB0_1275
	s_ashr_i32 s11, s10, 31
	v_ashrrev_i32_e32 v35, 31, v34
	s_lshl_b64 s[10:11], s[10:11], 15
	v_lshlrev_b64 v[34:35], 10, v[34:35]
	v_lshl_add_u64 v[34:35], v[34:35], 0, s[10:11]
	v_lshlrev_b64 v[38:39], 2, v[34:35]
	v_lshl_add_u64 v[34:35], s[42:43], 0, v[38:39]
	v_lshl_or_b32 v32, s17, 8, v32
	v_lshl_add_u64 v[34:35], v[34:35], 0, v[32:33]
	global_load_dwordx4 v[34:37], v[34:35], off
	v_pk_add_f32 v[30:31], v[30:31], 0 op_sel_hi:[1,0]
	v_pk_add_f32 v[28:29], v[28:29], 0 op_sel_hi:[1,0]
	v_pk_add_f32 v[26:27], v[30:31], v[26:27]
	v_pk_add_f32 v[24:25], v[28:29], v[24:25]
	v_pk_add_f32 v[22:23], v[26:27], v[22:23]
	v_pk_add_f32 v[20:21], v[24:25], v[20:21]
	v_pk_add_f32 v[18:19], v[22:23], v[18:19]
	v_pk_add_f32 v[16:17], v[20:21], v[16:17]
	v_pk_add_f32 v[14:15], v[18:19], v[14:15]
	v_pk_add_f32 v[12:13], v[16:17], v[12:13]
	v_pk_add_f32 v[10:11], v[14:15], v[10:11]
	v_pk_add_f32 v[8:9], v[12:13], v[8:9]
	v_pk_add_f32 v[6:7], v[10:11], v[6:7]
	v_pk_add_f32 v[4:5], v[8:9], v[4:5]
	v_lshl_add_u64 v[16:17], s[4:5], 0, v[38:39]
	v_pk_add_f32 v[2:3], v[6:7], v[2:3]
	v_pk_add_f32 v[0:1], v[4:5], v[0:1]
	v_lshl_add_u64 v[4:5], v[16:17], 0, v[32:33]
	s_waitcnt vmcnt(0)
	v_pk_add_f32 v[2:3], v[2:3], v[36:37]
	v_pk_add_f32 v[0:1], v[0:1], v[34:35]
	global_store_dwordx4 v[4:5], v[0:3], off
	s_branch .LBB0_1275
